# P2 gate prep: K-tile and q-tile loads of each unit issued together (4+4 in flight) instead of one serialized round trip per loop trip (v66 + prepld)
# speedup vs baseline: 1.0004x; 1.0004x over previous
.LBB0_311:
	v_ashrrev_i32_e32 v145, 5, v2
	v_mad_u64_u32 v[136:137], s[66:67], v145, s78, v[24:25]
	v_add_u32_e32 v146, s50, v145
	v_mad_i64_i32 v[128:129], s[66:67], v146, s81, v[0:1]
	v_add_u32_e32 v144, 0x200, v2
	v_ashrrev_i32_e32 v145, 5, v144
	v_mad_u64_u32 v[138:139], s[66:67], v145, s78, v[24:25]
	v_add_u32_e32 v146, s50, v145
	v_mad_i64_i32 v[130:131], s[66:67], v146, s81, v[0:1]
	v_add_u32_e32 v144, 0x400, v2
	v_ashrrev_i32_e32 v145, 5, v144
	v_mad_u64_u32 v[140:141], s[66:67], v145, s78, v[24:25]
	v_add_u32_e32 v146, s50, v145
	v_mad_i64_i32 v[132:133], s[66:67], v146, s81, v[0:1]
	v_add_u32_e32 v144, 0x600, v2
	v_ashrrev_i32_e32 v145, 5, v144
	v_mad_u64_u32 v[142:143], s[66:67], v145, s78, v[24:25]
	v_add_u32_e32 v146, s50, v145
	v_mad_i64_i32 v[134:135], s[66:67], v146, s81, v[0:1]
	global_load_dwordx4 v[112:115], v[128:129], off offset:2048
	global_load_dwordx4 v[116:119], v[130:131], off offset:2048
	global_load_dwordx4 v[120:123], v[132:133], off offset:2048
	global_load_dwordx4 v[124:127], v[134:135], off offset:2048
	global_load_dwordx4 v[148:151], v[128:129], off
	global_load_dwordx4 v[152:155], v[130:131], off
	global_load_dwordx4 v[156:159], v[132:133], off
	global_load_dwordx4 v[160:163], v[134:135], off
	s_waitcnt vmcnt(7)
	ds_write_b128 v136, v[112:115]
	s_waitcnt vmcnt(6)
	ds_write_b128 v138, v[116:119]
	s_waitcnt vmcnt(5)
	ds_write_b128 v140, v[120:123]
	s_waitcnt vmcnt(4)
	ds_write_b128 v142, v[124:127]

.LBB0_317:
	s_or_b64 exec, exec, s[66:67]
	s_barrier
	s_and_saveexec_b64 s[66:67], s[10:11]
	s_cbranch_execz .LBB0_320
	s_lshl_b32 s49, s51, 1
	s_add_u32 s68, s33, s49
	s_addc_u32 s69, s54, 0
	v_lshl_add_u64 v[0:1], s[68:69], 0, v[20:21]
	s_mov_b64 s[68:69], 0
	v_mov_b32_e32 v2, v16
	s_waitcnt vmcnt(0)
.LBB0_319:
	v_ashrrev_i32_e32 v8, 5, v2
	v_add_u32_e32 v9, 0x200, v2
	v_cmp_lt_i32_e32 vcc, s93, v2
	v_add_u32_e32 v2, s50, v8
	v_mad_i64_i32 v[2:3], s[54:55], v2, s81, v[0:1]
	v_mov_b32_e32 v4, v148
	v_mov_b32_e32 v5, v149
	v_mov_b32_e32 v6, v150
	v_mov_b32_e32 v7, v151
	v_mul_lo_u32 v12, v8, s78
	v_mad_u64_u32 v[94:95], s[54:55], v8, s75, v[26:27]
	v_add_u32_e32 v3, v24, v12
	v_mov_b32_e32 v2, v9
	ds_read_b128 v[8:11], v94 offset:38928
	v_add_u32_e32 v20, v41, v12
	ds_read_b128 v[12:15], v3
	ds_read_b128 v[94:97], v94 offset:38912
	s_or_b64 s[68:69], vcc, s[68:69]
	s_waitcnt lgkmcnt(2)
	v_mul_f32_e32 v31, 0x3fb8aa3b, v8
	v_mul_f32_e32 v93, 0x3fb8aa3b, v9
	v_mul_f32_e32 v99, 0x3fb8aa3b, v11
	v_mul_f32_e32 v8, 0xbfb8aa3b, v8
	v_mul_f32_e32 v9, 0xbfb8aa3b, v9
	v_mul_f32_e32 v11, 0xbfb8aa3b, v11
	s_waitcnt lgkmcnt(0)
	v_mul_f32_e32 v100, 0x3fb8aa3b, v94
	v_mul_f32_e32 v101, 0x3fb8aa3b, v95
	v_mul_f32_e32 v103, 0x3fb8aa3b, v97
	v_mul_f32_e32 v94, 0xbfb8aa3b, v94
	v_mul_f32_e32 v95, 0xbfb8aa3b, v95
	v_mul_f32_e32 v97, 0xbfb8aa3b, v97
	v_exp_f32_e32 v8, v8
	v_exp_f32_e32 v9, v9
	v_exp_f32_e32 v11, v11
	v_exp_f32_e32 v94, v94
	v_exp_f32_e32 v95, v95
	v_exp_f32_e32 v97, v97
	v_mul_f32_e32 v98, 0x3fb8aa3b, v10
	v_mul_f32_e32 v10, 0xbfb8aa3b, v10
	v_mul_f32_e32 v102, 0x3fb8aa3b, v96
	v_exp_f32_e32 v93, v93
	v_exp_f32_e32 v99, v99
	v_mul_f32_e32 v96, 0xbfb8aa3b, v96
	v_exp_f32_e32 v101, v101
	v_exp_f32_e32 v103, v103
	v_exp_f32_e32 v31, v31
	v_exp_f32_e32 v98, v98
	v_exp_f32_e32 v10, v10
	v_exp_f32_e32 v100, v100
	v_exp_f32_e32 v102, v102
	v_exp_f32_e32 v96, v96
	v_lshlrev_b32_e32 v104, 16, v12
	v_and_b32_e32 v12, 0xffff0000, v12
	v_lshlrev_b32_e32 v105, 16, v13
	v_and_b32_e32 v13, 0xffff0000, v13
	v_lshlrev_b32_e32 v106, 16, v14
	v_and_b32_e32 v14, 0xffff0000, v14
	v_lshlrev_b32_e32 v107, 16, v15
	v_and_b32_e32 v15, 0xffff0000, v15
	v_mul_f32_e32 v106, v8, v106
	v_mul_f32_e32 v14, v9, v14
	v_mul_f32_e32 v11, v11, v15
	v_mul_f32_e32 v8, v94, v104
	v_mul_f32_e32 v9, v95, v12
	v_mul_f32_e32 v12, v97, v13
	v_mul_f32_e32 v107, v10, v107
	v_mul_f32_e32 v10, v96, v105
	s_waitcnt vmcnt(0)
	v_lshlrev_b32_e32 v13, 16, v4
	v_and_b32_e32 v4, 0xffff0000, v4
	v_lshlrev_b32_e32 v15, 16, v5
	v_and_b32_e32 v5, 0xffff0000, v5
	v_lshlrev_b32_e32 v94, 16, v6
	v_and_b32_e32 v6, 0xffff0000, v6
	v_lshlrev_b32_e32 v95, 16, v7
	v_and_b32_e32 v7, 0xffff0000, v7
	v_mul_f32_e32 v4, v101, v4
	v_mul_f32_e32 v5, v103, v5
	v_mul_f32_e32 v6, v93, v6
	v_mul_f32_e32 v7, v99, v7
	v_mul_f32_e32 v13, v100, v13
	v_mul_f32_e32 v15, v102, v15
	v_mul_f32_e32 v31, v31, v94
	v_mul_f32_e32 v93, v98, v95
	v_cvt_pk_bf16_f32 v4, v13, v4
	v_cvt_pk_bf16_f32 v5, v15, v5
	v_cvt_pk_bf16_f32 v6, v31, v6
	v_cvt_pk_bf16_f32 v7, v93, v7
	v_cvt_pk_bf16_f32 v8, v8, v9
	v_cvt_pk_bf16_f32 v9, v10, v12
	v_cvt_pk_bf16_f32 v10, v106, v14
	v_cvt_pk_bf16_f32 v11, v107, v11
	ds_write_b128 v20, v[4:7]
	ds_write_b128 v3, v[8:11]
	v_mov_b32_e32 v148, v152
	v_mov_b32_e32 v149, v153
	v_mov_b32_e32 v150, v154
	v_mov_b32_e32 v151, v155
	v_mov_b32_e32 v152, v156
	v_mov_b32_e32 v153, v157
	v_mov_b32_e32 v154, v158
	v_mov_b32_e32 v155, v159
	v_mov_b32_e32 v156, v160
	v_mov_b32_e32 v157, v161
	v_mov_b32_e32 v158, v162
	v_mov_b32_e32 v159, v163
	s_andn2_b64 exec, exec, s[68:69]
	s_cbranch_execnz .LBB0_319

.LBB0_368:
	v_ashrrev_i32_e32 v145, 5, v1
	v_mad_u64_u32 v[136:137], s[68:69], v145, s82, v[22:23]
	v_add_u32_e32 v146, s50, v145
	v_mad_i64_i32 v[128:129], s[68:69], v146, s84, v[2:3]
	v_add_u32_e32 v144, 0x200, v1
	v_ashrrev_i32_e32 v145, 5, v144
	v_mad_u64_u32 v[138:139], s[68:69], v145, s82, v[22:23]
	v_add_u32_e32 v146, s50, v145
	v_mad_i64_i32 v[130:131], s[68:69], v146, s84, v[2:3]
	v_add_u32_e32 v144, 0x400, v1
	v_ashrrev_i32_e32 v145, 5, v144
	v_mad_u64_u32 v[140:141], s[68:69], v145, s82, v[22:23]
	v_add_u32_e32 v146, s50, v145
	v_mad_i64_i32 v[132:133], s[68:69], v146, s84, v[2:3]
	v_add_u32_e32 v144, 0x600, v1
	v_ashrrev_i32_e32 v145, 5, v144
	v_mad_u64_u32 v[142:143], s[68:69], v145, s82, v[22:23]
	v_add_u32_e32 v146, s50, v145
	v_mad_i64_i32 v[134:135], s[68:69], v146, s84, v[2:3]
	global_load_dwordx4 v[112:115], v[128:129], off offset:2048
	global_load_dwordx4 v[116:119], v[130:131], off offset:2048
	global_load_dwordx4 v[120:123], v[132:133], off offset:2048
	global_load_dwordx4 v[124:127], v[134:135], off offset:2048
	global_load_dwordx4 v[148:151], v[128:129], off
	global_load_dwordx4 v[152:155], v[130:131], off
	global_load_dwordx4 v[156:159], v[132:133], off
	global_load_dwordx4 v[160:163], v[134:135], off
	s_waitcnt vmcnt(7)
	ds_write_b128 v136, v[112:115]
	s_waitcnt vmcnt(6)
	ds_write_b128 v138, v[116:119]
	s_waitcnt vmcnt(5)
	ds_write_b128 v140, v[120:123]
	s_waitcnt vmcnt(4)
	ds_write_b128 v142, v[124:127]

.LBB0_374:
	s_or_b64 exec, exec, s[42:43]
	s_barrier
	s_and_saveexec_b64 s[42:43], s[10:11]
	s_cbranch_execz .LBB0_377
	s_lshl_b32 s55, s78, 1
	s_add_u32 s68, s51, s55
	s_addc_u32 s69, s54, 0
	v_mov_b32_e32 v1, v19
	v_lshl_add_u64 v[0:1], s[68:69], 0, v[0:1]
	s_mov_b64 s[68:69], 0
	v_mov_b32_e32 v2, v16
	s_waitcnt vmcnt(0)
.LBB0_376:
	v_ashrrev_i32_e32 v8, 5, v2
	v_add_u32_e32 v9, 0x200, v2
	v_cmp_lt_i32_e32 vcc, s96, v2
	v_add_u32_e32 v2, s50, v8
	v_mad_i64_i32 v[2:3], s[54:55], v2, s84, v[0:1]
	v_mov_b32_e32 v4, v148
	v_mov_b32_e32 v5, v149
	v_mov_b32_e32 v6, v150
	v_mov_b32_e32 v7, v151
	v_mul_lo_u32 v12, v8, s82
	v_mad_u64_u32 v[94:95], s[54:55], v8, s79, v[24:25]
	v_add_u32_e32 v3, v22, v12
	v_mov_b32_e32 v2, v9
	ds_read_b128 v[8:11], v94 offset:38928
	v_add_u32_e32 v29, v40, v12
	ds_read_b128 v[12:15], v3
	ds_read_b128 v[94:97], v94 offset:38912
	s_or_b64 s[68:69], vcc, s[68:69]
	s_waitcnt lgkmcnt(2)
	v_mul_f32_e32 v93, 0x3fb8aa3b, v8
	v_mul_f32_e32 v98, 0x3fb8aa3b, v9
	v_mul_f32_e32 v100, 0x3fb8aa3b, v11
	v_mul_f32_e32 v8, 0xbfb8aa3b, v8
	v_mul_f32_e32 v9, 0xbfb8aa3b, v9
	v_mul_f32_e32 v11, 0xbfb8aa3b, v11
	s_waitcnt lgkmcnt(0)
	v_mul_f32_e32 v101, 0x3fb8aa3b, v94
	v_mul_f32_e32 v102, 0x3fb8aa3b, v95
	v_mul_f32_e32 v104, 0x3fb8aa3b, v97
	v_mul_f32_e32 v94, 0xbfb8aa3b, v94
	v_mul_f32_e32 v95, 0xbfb8aa3b, v95
	v_mul_f32_e32 v97, 0xbfb8aa3b, v97
	v_exp_f32_e32 v8, v8
	v_exp_f32_e32 v9, v9
	v_exp_f32_e32 v11, v11
	v_exp_f32_e32 v94, v94
	v_exp_f32_e32 v95, v95
	v_exp_f32_e32 v97, v97
	v_mul_f32_e32 v99, 0x3fb8aa3b, v10
	v_mul_f32_e32 v10, 0xbfb8aa3b, v10
	v_mul_f32_e32 v103, 0x3fb8aa3b, v96
	v_exp_f32_e32 v98, v98
	v_exp_f32_e32 v100, v100
	v_mul_f32_e32 v96, 0xbfb8aa3b, v96
	v_exp_f32_e32 v102, v102
	v_exp_f32_e32 v104, v104
	v_exp_f32_e32 v93, v93
	v_exp_f32_e32 v99, v99
	v_exp_f32_e32 v10, v10
	v_exp_f32_e32 v101, v101
	v_exp_f32_e32 v103, v103
	v_exp_f32_e32 v96, v96
	v_lshlrev_b32_e32 v105, 16, v12
	v_and_b32_e32 v12, 0xffff0000, v12
	v_lshlrev_b32_e32 v106, 16, v13
	v_and_b32_e32 v13, 0xffff0000, v13
	v_lshlrev_b32_e32 v107, 16, v14
	v_and_b32_e32 v14, 0xffff0000, v14
	v_lshlrev_b32_e32 v108, 16, v15
	v_and_b32_e32 v15, 0xffff0000, v15
	v_mul_f32_e32 v107, v8, v107
	v_mul_f32_e32 v14, v9, v14
	v_mul_f32_e32 v11, v11, v15
	v_mul_f32_e32 v8, v94, v105
	v_mul_f32_e32 v9, v95, v12
	v_mul_f32_e32 v12, v97, v13
	v_mul_f32_e32 v108, v10, v108
	v_mul_f32_e32 v10, v96, v106
	s_waitcnt vmcnt(0)
	v_lshlrev_b32_e32 v13, 16, v4
	v_and_b32_e32 v4, 0xffff0000, v4
	v_lshlrev_b32_e32 v15, 16, v5
	v_and_b32_e32 v5, 0xffff0000, v5
	v_lshlrev_b32_e32 v94, 16, v6
	v_and_b32_e32 v6, 0xffff0000, v6
	v_lshlrev_b32_e32 v95, 16, v7
	v_and_b32_e32 v7, 0xffff0000, v7
	v_mul_f32_e32 v4, v102, v4
	v_mul_f32_e32 v5, v104, v5
	v_mul_f32_e32 v6, v98, v6
	v_mul_f32_e32 v7, v100, v7
	v_mul_f32_e32 v13, v101, v13
	v_mul_f32_e32 v15, v103, v15
	v_mul_f32_e32 v93, v93, v94
	v_mul_f32_e32 v94, v99, v95
	v_cvt_pk_bf16_f32 v4, v13, v4
	v_cvt_pk_bf16_f32 v5, v15, v5
	v_cvt_pk_bf16_f32 v6, v93, v6
	v_cvt_pk_bf16_f32 v7, v94, v7
	v_cvt_pk_bf16_f32 v8, v8, v9
	v_cvt_pk_bf16_f32 v9, v10, v12
	v_cvt_pk_bf16_f32 v10, v107, v14
	v_cvt_pk_bf16_f32 v11, v108, v11
	ds_write_b128 v29, v[4:7]
	ds_write_b128 v3, v[8:11]
	v_mov_b32_e32 v148, v152
	v_mov_b32_e32 v149, v153
	v_mov_b32_e32 v150, v154
	v_mov_b32_e32 v151, v155
	v_mov_b32_e32 v152, v156
	v_mov_b32_e32 v153, v157
	v_mov_b32_e32 v154, v158
	v_mov_b32_e32 v155, v159
	v_mov_b32_e32 v156, v160
	v_mov_b32_e32 v157, v161
	v_mov_b32_e32 v158, v162
	v_mov_b32_e32 v159, v163
	s_andn2_b64 exec, exec, s[68:69]
	s_cbranch_execnz .LBB0_376
